# helper priority reset also on the last chunk's early exit
# speedup vs baseline: 1.0061x; 1.0036x over previous
.Lmy_f_nofl:
	s_cmp_eq_u32 s65, 63
	s_cbranch_scc0 .Lmy_f_hl2
	s_setprio 0
	s_branch .LBB0_655

.Lmy_ck_drE_h:
	s_waitcnt lgkmcnt(0)
	s_bfe_u32 s96, s62, 0x20006
	s_and_b32 s97, s96, 1
	s_mul_i32 s97, s97, 0x2700
	s_mov_b32 s101, 0x1c000
	s_mov_b32 s100, 0x6100
	s_bitcmp0_b32 s65, 0
	s_cselect_b32 s101, 0xe000, s101
	s_cselect_b32 s100, 0x4e00, s100
	s_cmp_gt_u32 s96, 1
	s_cselect_b32 s100, s100, 0
	s_add_i32 s97, s97, s101
	s_add_i32 s97, s97, s100
	s_mov_b32 s96, s97
	v_and_b32_e32 v72, 3, v233
	v_lshrrev_b32_e32 v73, 2, v233
	v_lshlrev_b32_e32 v72, 2, v72
	v_lshl_add_u32 v72, v73, 8, v72
	v_lshl_add_u32 v72, v234, 6, v72
	s_add_i32 s97, s96, 0x1000
	v_add_u32_e32 v78, s97, v72
	v_xor_b32_e32 v79, v224, v234
	v_lshl_add_u32 v79, v79, 4, s96
	ds_read_b128 v[96:99], v79
	ds_read_b128 v[100:103], v79 offset:1024
	ds_read_b128 v[104:107], v79 offset:2048
	ds_read_b128 v[108:111], v79 offset:3072
	ds_read_b32 v80, v78
	ds_read_b32 v81, v78 offset:16
	ds_read_b32 v82, v78 offset:32
	ds_read_b32 v83, v78 offset:48
	ds_read_b32 v84, v78 offset:1024
	ds_read_b32 v85, v78 offset:1040
	ds_read_b32 v86, v78 offset:1056
	ds_read_b32 v87, v78 offset:1072
	ds_read_b32 v88, v78 offset:2048
	ds_read_b32 v89, v78 offset:2064
	ds_read_b32 v90, v78 offset:2080
	ds_read_b32 v91, v78 offset:2096
	ds_read_b32 v92, v78 offset:3072
	ds_read_b32 v93, v78 offset:3088
	ds_read_b32 v94, v78 offset:3104
	ds_read_b32 v95, v78 offset:3120
	v_lshl_add_u32 v74, v224, 2, s96
	ds_write_b32 v74, v235 offset:9728
	v_add_u32_e32 v75, -1, v233
	v_mov_b32_e32 v76, -1
	v_cndmask_b32_e64 v75, v76, v75, s[98:99]
	v_cmp_lt_u32_e64 s[100:101], 7, v233
	v_add_u32_e32 v76, -8, v233
	v_and_b32_e32 v77, 1, v234
	v_cndmask_b32_e64 v75, v75, v76, s[100:101]
	v_lshlrev_b32_e32 v77, 2, v77
	v_sub_u32_e32 v76, v75, v77
	v_lshlrev_b32_e32 v77, 2, v234
	v_sub_u32_e32 v77, v233, v77
	v_add_u32_e32 v77, -1, v77
	s_waitcnt lgkmcnt(15)
	v_mfma_f32_16x16x4_f32 v[244:247], v80, v96, 0
	v_mfma_f32_16x16x4_f32 v[240:243], v81, v97, 0
	s_waitcnt lgkmcnt(14)
	v_mfma_f32_16x16x4_f32 v[244:247], v82, v98, v[244:247]
	s_waitcnt lgkmcnt(13)
	v_mfma_f32_16x16x4_f32 v[240:243], v83, v99, v[240:243]
	s_waitcnt lgkmcnt(12)
	v_mfma_f32_16x16x4_f32 v[244:247], v84, v100, v[244:247]
	s_waitcnt lgkmcnt(11)
	v_mfma_f32_16x16x4_f32 v[240:243], v85, v101, v[240:243]
	s_waitcnt lgkmcnt(10)
	v_mfma_f32_16x16x4_f32 v[244:247], v86, v102, v[244:247]
	s_waitcnt lgkmcnt(9)
	v_mfma_f32_16x16x4_f32 v[240:243], v87, v103, v[240:243]
	s_waitcnt lgkmcnt(8)
	v_mfma_f32_16x16x4_f32 v[244:247], v88, v104, v[244:247]
	s_waitcnt lgkmcnt(7)
	v_mfma_f32_16x16x4_f32 v[240:243], v89, v105, v[240:243]
	s_waitcnt lgkmcnt(6)
	v_mfma_f32_16x16x4_f32 v[244:247], v90, v106, v[244:247]
	s_waitcnt lgkmcnt(5)
	v_mfma_f32_16x16x4_f32 v[240:243], v91, v107, v[240:243]
	s_waitcnt lgkmcnt(4)
	v_mfma_f32_16x16x4_f32 v[244:247], v92, v108, v[244:247]
	s_waitcnt lgkmcnt(3)
	v_mfma_f32_16x16x4_f32 v[240:243], v93, v109, v[240:243]
	s_waitcnt lgkmcnt(2)
	v_mfma_f32_16x16x4_f32 v[244:247], v94, v110, v[244:247]
	s_waitcnt lgkmcnt(1)
	v_mfma_f32_16x16x4_f32 v[240:243], v95, v111, v[240:243]
	s_nop 9
	v_add_f32_e32 v244, v244, v240
	v_add_f32_e32 v245, v245, v241
	v_add_f32_e32 v246, v246, v242
	v_add_f32_e32 v247, v247, v243
	v_cmp_le_i32_e64 s[96:97], 0, v76
	v_cmp_le_i32_e64 s[100:101], 1, v76
	s_nop 0
	v_cndmask_b32_e64 v128, 0, v244, s[96:97]
	v_cndmask_b32_e64 v129, 0, v245, s[100:101]
	v_cmp_le_i32_e64 s[96:97], 2, v76
	v_cmp_le_i32_e64 s[100:101], 3, v76
	s_nop 0
	v_cndmask_b32_e64 v130, 0, v246, s[96:97]
	v_cndmask_b32_e64 v131, 0, v247, s[100:101]
	s_bfe_u32 s96, s62, 0x20006
	s_and_b32 s97, s96, 1
	s_mul_i32 s97, s97, 0x2700
	s_mov_b32 s101, 0x1c000
	s_mov_b32 s100, 0x6100
	s_bitcmp0_b32 s65, 0
	s_cselect_b32 s101, 0xe000, s101
	s_cselect_b32 s100, 0x4e00, s100
	s_cmp_gt_u32 s96, 1
	s_cselect_b32 s100, s100, 0
	s_add_i32 s97, s97, s101
	s_add_i32 s97, s97, s100
	v_xor_b32_e32 v74, v224, v234
	v_lshl_add_u32 v74, v74, 4, s97
	ds_write_b128 v74, v[128:131] offset:8448
	v_lshlrev_b32_e32 v75, 7, v234
	v_lshl_add_u32 v75, v233, 2, v75
	v_add_u32_e32 v75, s97, v75
	v_cmp_le_i32_e64 s[96:97], 0, v77
	v_cmp_le_i32_e64 s[100:101], 1, v77
	s_nop 0
	v_cndmask_b32_e64 v132, 0, v244, s[96:97]
	v_cndmask_b32_e64 v133, 0, v245, s[100:101]
	v_cmp_le_i32_e64 s[96:97], 2, v77
	v_cmp_le_i32_e64 s[100:101], 3, v77
	s_nop 0
	v_cndmask_b32_e64 v134, 0, v246, s[96:97]
	v_cndmask_b32_e64 v135, 0, v247, s[100:101]
	s_mov_b64 exec, 0x00ff00ff
	ds_write_b32 v75, v132 offset:9472
	ds_write_b32 v75, v133 offset:9504
	ds_write_b32 v75, v134 offset:9536
	ds_write_b32 v75, v135 offset:9568
	s_mov_b64 exec, -1
	s_setprio 0
	s_branch .LBB0_655
	s_nop 0
	s_nop 0
	s_nop 0
	s_nop 0
	s_nop 0
	s_nop 0
	s_nop 0
	s_nop 0
	s_nop 0
	s_nop 0
	s_nop 0
	s_nop 0
	s_nop 0
	s_nop 0
	s_nop 0
	s_nop 0
	s_nop 0
	s_nop 0
	s_nop 0
	s_nop 0
	s_nop 0
	s_nop 0
	s_nop 0
	s_nop 0
	s_nop 0
	s_nop 0
	s_nop 0
	s_nop 0
	s_nop 0
	s_nop 0
	s_nop 0
	s_nop 0
	s_nop 0
	s_nop 0
.LBB0_674:
	s_cmp_lt_i32 s52, 6
	s_cselect_b64 s[46:47], -1, 0
	s_cmp_gt_i32 s52, 5
	s_cselect_b64 s[4:5], -1, 0
	s_cmp_lt_i32 s53, 6
	s_cselect_b64 s[6:7], -1, 0
	s_or_b64 s[4:5], s[4:5], s[6:7]
	s_and_b64 vcc, exec, s[4:5]
	s_cbranch_vccnz .LBB0_753
	s_mov_b64 s[4:5], s[0:1]
	s_load_dwordx2 s[48:49], s[4:5], 0xd0
	s_load_dwordx2 s[50:51], s[4:5], 0x38
	s_load_dwordx8 s[36:43], s[4:5], 0x88
	v_mbcnt_lo_u32_b32 v0, -1, 0
	v_mbcnt_hi_u32_b32 v0, -1, v0
	s_waitcnt vmcnt(0)
	v_add_u32_e32 v32, s62, v0
	s_andn2_b64 vcc, exec, s[44:45]
	s_waitcnt lgkmcnt(0)
	s_cbranch_vccnz .LBB0_721
	s_waitcnt vmcnt(0)
	v_cmp_eq_u32_e32 vcc, 0, v32
	s_barrier
	s_and_saveexec_b64 s[44:45], vcc
	s_cbranch_execz .LBB0_720
	s_add_i32 s4, 0, 0x22000
	v_mov_b32_e32 v0, s4
	s_waitcnt vmcnt(0) expcnt(0) lgkmcnt(0)
	s_getreg_b32 s3, hwreg(HW_REG_XCC_ID, 0, 4)
	ds_read_b32 v2, v0
	s_add_i32 s4, 0, 0x22004
	v_mov_b32_e32 v0, s4
	ds_read_b32 v0, v0
	s_and_b32 s3, s3, 15
	s_waitcnt lgkmcnt(1)
	v_cmp_ne_u32_e32 vcc, 0, v2
	s_cbranch_vccnz .LBB0_691
	s_add_u32 s4, s48, 0x1b900200
	s_addc_u32 s5, s49, 0
	s_add_u32 s8, s48, 0x1b900400
	s_addc_u32 s9, s49, 0
	s_add_u32 s10, s48, 0x1b900500
	s_addc_u32 s11, s49, 0
	s_add_u32 s12, s48, 0x1b900600
	s_addc_u32 s13, s49, 0
	s_add_u32 s14, s48, 0x1b900700
	s_addc_u32 s15, s49, 0
	s_add_u32 s16, s48, 0x1b900800
	s_addc_u32 s17, s49, 0
	s_add_u32 s18, s48, 0x1b900900
	s_addc_u32 s19, s49, 0
	s_add_u32 s20, s48, 0x1b900a00
	s_addc_u32 s21, s49, 0
	s_add_u32 s22, s48, 0x1b900b00
	s_addc_u32 s23, s49, 0
	s_add_u32 s26, s48, 0x1b900c00
	s_addc_u32 s27, s49, 0
	s_add_u32 s28, s48, 0x1b900d00
	s_addc_u32 s29, s49, 0
	s_add_u32 s30, s48, 0x1b900e00
	s_addc_u32 s31, s49, 0
	s_add_u32 s34, s48, 0x1b900f00
	s_addc_u32 s35, s49, 0
	s_add_u32 s54, s48, 0x1b901000
	s_addc_u32 s55, s49, 0
	s_add_u32 s56, s48, 0x1b901100
	s_addc_u32 s57, s49, 0
	s_add_u32 s58, s48, 0x1b901200
	s_addc_u32 s59, s49, 0
	s_add_u32 s60, s48, 0x1b901300
	s_addc_u32 s61, s49, 0
	s_mov_b32 s24, 1
	s_mov_b64 s[6:7], 0
	s_waitcnt lgkmcnt(0)
	v_mov_b64_e32 v[0:1], s[8:9]
	v_mov_b64_e32 v[2:3], s[10:11]
	v_mov_b64_e32 v[4:5], s[12:13]
	v_mov_b64_e32 v[6:7], s[14:15]
	v_mov_b64_e32 v[8:9], s[16:17]
	v_mov_b64_e32 v[10:11], s[18:19]
	v_mov_b64_e32 v[12:13], s[20:21]
	v_mov_b64_e32 v[14:15], s[22:23]
	v_mov_b64_e32 v[16:17], s[26:27]
	v_mov_b64_e32 v[18:19], s[28:29]
	v_mov_b64_e32 v[20:21], s[30:31]
	v_mov_b64_e32 v[22:23], s[34:35]
	v_mov_b64_e32 v[24:25], s[54:55]
	v_mov_b64_e32 v[26:27], s[56:57]
	v_mov_b64_e32 v[28:29], s[58:59]
	v_mov_b64_e32 v[30:31], s[60:61]
	s_branch .LBB0_681
